# diff QK segment: K-fragment reads back to need-ordered just-in-time issue (distinct registers kept) instead of all up front
# speedup vs baseline: 1.0084x; 1.0084x over previous
; #define SBAR() __builtin_amdgcn_sched_barrier(0)
; #define KWRITE(b, src0, src1) do { if constexpr (ND0 == 4) { *(bf16x8*)(K_lds + (b) * SHM_K + KSWZ(kr, kcb)) = src0; } \
;     else { int kc = sc * 2; *(bf16x8*)(K_lds + (b) * SHM_K + KSWZ(sr, kc)) = src0; *(bf16x8*)(K_lds + (b) * SHM_K + KSWZ(32 + sr, kc)) = src1; } } while (0)
; #define SLOAD_B(k0) do { vs0b = *reinterpret_cast<const bf16x8*>(&Vh[(long)((k0) + sr) * LDK + sc]); vs1b = *reinterpret_cast<const bf16x8*>(&Vh[(long)((k0) + 32 + sr) * LDK + sc]); KLOAD(ks0b, ks1b, k0); } while (0)
; #define PSM(P0, P1, MN, AL) do { if constexpr (PRE) partialSM_pre(P0, P1, m_reg, AL, 11.541560327111707f); else partialSM(P0, P1, m_reg, MN, AL, C, thr_raw); } while (0)
; __device__ __forceinline__ void finishSM(f32x16& p0, f32x16& p1, float alpha, float& l_reg, bf16x8& pa0, bf16x8& pa1, bf16x8& pa2, bf16x8& pa3) {
; #pragma unroll
;   for (int r = 0; r < 16; ++r) p1[r] = __builtin_amdgcn_exp2f(p1[r]);
;   float ps = 0;
; #pragma unroll
;   for (int r = 0; r < 16; ++r) ps += p0[r];
; #pragma unroll
;   for (int r = 0; r < 16; ++r) ps += p1[r];
;   { auto rr = __builtin_amdgcn_permlane32_swap(__float_as_uint(ps), __float_as_uint(ps), false, false);
;     ps = __uint_as_float(rr[0]) + __uint_as_float(rr[1]); }
;   l_reg = l_reg * alpha + ps;
;     ...
;   PK4(p0, 0, pa0); PK4(p0, 8, pa1); PK4(p1, 0, pa2); PK4(p1, 8, pa3);
;     ...
; }
; template <int ND0>
; __device__ __forceinline__ void qkt(f32x16& p0, f32x16& p1, const char* Ks, const bf16x8* qr, int r32, int hi) {
;   p0 = f32x16{}; p1 = f32x16{};
; #pragma unroll
;   for (int d0 = 0; d0 < ND0; ++d0) { int cb = (d0 * 16 + hi * 8) * 2;
;     bf16x8 b0 = *reinterpret_cast<const bf16x8*>(Ks + KSWZ(r32, cb));
;     bf16x8 b1 = *reinterpret_cast<const bf16x8*>(Ks + KSWZ(32 + r32, cb));
;     p0 = __builtin_amdgcn_mfma_f32_32x32x16_bf16(b0, qr[d0], p0, 0, 0, 0);
;     p1 = __builtin_amdgcn_mfma_f32_32x32x16_bf16(b1, qr[d0], p1, 0, 0, 0); }
; }
; template <int ND0, int LDQ, int LDK, int LDO> ...
;     ...
;     SBAR(); qkt<ND0>(pB0, pB1, Kq1, qr, r32, hi);
;     finishSM(pA0, pA1, alA, l_reg, pa0, pa1, pa2, pa3); SBAR();
;     SLOAD_B((j + 2) * KVBLK); SBAR();
;     pv_d0(o, vb0, pa0, pa1, pa2, pa3); KWRITE(0, ks0a, ks1a); PSM(pB0, pB1, mnB, alB);
.LBB0_214:
	ds_read_b128 v[202:205], v198 offset:49152
	ds_read_b128 v[208:211], v198 offset:57344
	v_exp_f32_e32 v150, v64
	s_waitcnt lgkmcnt(2)
	v_mfma_f32_32x32x16_bf16 v[96:111], v[80:83], v[126:129], 0
	v_add_f32_e32 v64, v206, v176
	v_add_f32_e32 v64, v174, v64
	v_add_f32_e32 v64, v177, v64
	v_add_f32_e32 v64, v152, v64
	v_add_f32_e32 v64, v175, v64
	v_add_f32_e32 v64, v151, v64
	v_add_f32_e32 v64, v153, v64
	v_mfma_f32_32x32x16_bf16 v[80:95], v[84:87], v[126:129], 0
	v_add_f32_e32 v64, v147, v64
	v_add_f32_e32 v64, v149, v64
	v_add_f32_e32 v64, v145, v64
	v_add_f32_e32 v64, v148, v64
	v_add_f32_e32 v64, v143, v64
	v_add_f32_e32 v64, v146, v64
	v_add_f32_e32 v64, v142, v64
	s_waitcnt lgkmcnt(0)
	v_mfma_f32_32x32x16_bf16 v[96:111], v[202:205], v[122:125], v[96:111]
	v_add_f32_e32 v64, v144, v64
	v_exp_f32_e32 v207, v68
	v_add_f32_e32 v64, v150, v64
	v_exp_f32_e32 v212, v73
	v_exp_f32_e32 v213, v74
	v_exp_f32_e32 v214, v75
	v_exp_f32_e32 v215, v76
	v_mfma_f32_32x32x16_bf16 v[80:95], v[208:211], v[122:125], v[80:95]
	ds_read_b128 v[222:225], v199 offset:49152
	ds_read_b128 v[234:237], v199 offset:57344
	v_exp_f32_e32 v216, v77
	v_exp_f32_e32 v217, v78
	v_exp_f32_e32 v79, v79
	s_waitcnt lgkmcnt(0)
	v_mfma_f32_32x32x16_bf16 v[96:111], v[222:225], v[118:121], v[96:111]
	v_mfma_f32_32x32x16_bf16 v[80:95], v[234:237], v[118:121], v[80:95]
	ds_read_b128 v[238:241], v196 offset:49152
	ds_read_b128 v[244:247], v196 offset:57344
	s_waitcnt lgkmcnt(0)
	v_mfma_f32_32x32x16_bf16 v[96:111], v[238:241], v[114:117], v[96:111]
	v_exp_f32_e32 v203, v65
	v_exp_f32_e32 v204, v66
	v_exp_f32_e32 v205, v67
	v_add_f32_e32 v64, v203, v64
	v_add_f32_e32 v64, v204, v64
	v_add_f32_e32 v64, v205, v64
	v_mfma_f32_32x32x16_bf16 v[80:95], v[244:247], v[114:117], v[80:95]
	v_exp_f32_e32 v208, v69
	v_exp_f32_e32 v209, v70
	v_exp_f32_e32 v210, v71
	v_exp_f32_e32 v211, v72
	v_add_f32_e32 v64, v207, v64
	v_add_f32_e32 v64, v208, v64
	v_add_f32_e32 v64, v209, v64
	v_add_f32_e32 v64, v210, v64
	v_add_f32_e32 v64, v211, v64
	v_add_f32_e32 v64, v212, v64
	v_add_f32_e32 v64, v213, v64
	v_add_f32_e32 v64, v214, v64
	v_add_f32_e32 v64, v215, v64
	v_add_f32_e32 v64, v216, v64
	v_add_f32_e32 v64, v217, v64
	v_add_f32_e32 v201, v79, v64
	v_mov_b32_e32 v202, v201
	v_cvt_pk_bf16_f32 v64, v176, v206
	v_cvt_pk_bf16_f32 v65, v174, v177
	v_cvt_pk_bf16_f32 v66, v152, v175
	v_cvt_pk_bf16_f32 v67, v151, v153
	v_cvt_pk_bf16_f32 v68, v147, v149
	v_cvt_pk_bf16_f32 v69, v145, v148
	v_cvt_pk_bf16_f32 v70, v143, v146
	v_cvt_pk_bf16_f32 v71, v142, v144
	v_cvt_pk_bf16_f32 v72, v150, v203
	v_cvt_pk_bf16_f32 v73, v204, v205
	v_cvt_pk_bf16_f32 v74, v207, v208
	v_cvt_pk_bf16_f32 v75, v209, v210
	v_cvt_pk_bf16_f32 v76, v211, v212
	v_cvt_pk_bf16_f32 v77, v213, v214
	v_cvt_pk_bf16_f32 v78, v215, v216
	v_cvt_pk_bf16_f32 v79, v217, v79
	v_permlane32_swap_b32_e32 v201, v202
	v_permlane32_swap_b32_e32 v64, v66
	v_permlane32_swap_b32_e32 v65, v67
	v_permlane32_swap_b32_e32 v68, v70
	v_permlane32_swap_b32_e32 v69, v71
	v_permlane32_swap_b32_e32 v72, v74
	v_permlane32_swap_b32_e32 v73, v75
	v_permlane32_swap_b32_e32 v76, v78
	v_permlane32_swap_b32_e32 v77, v79
	global_load_dwordx4 v[142:145], v[172:173], off
	v_lshl_add_u64 v[174:175], v[172:173], 0, s[34:35]
	global_load_dwordx4 v[146:149], v[174:175], off
	global_load_dwordx4 v[150:153], v[170:171], off offset:2048
	v_lshl_add_u64 v[172:173], v[172:173], 0, s[46:47]
	v_lshl_add_u64 v[170:171], v[170:171], 0, s[46:47]
	v_cmp_neq_f32_e32 vcc, 0, v191
	ds_read_b64_tr_b16 v[204:205], v192 offset:0
	ds_read_b64_tr_b16 v[206:207], v192 offset:0x800
	ds_read_b64_tr_b16 v[208:209], v192 offset:0x1000
	ds_read_b64_tr_b16 v[210:211], v192 offset:0x1800
	ds_read_b64_tr_b16 v[212:213], v192 offset:0x2000
	ds_read_b64_tr_b16 v[214:215], v192 offset:0x2800
	ds_read_b64_tr_b16 v[216:217], v192 offset:0x3000
	ds_read_b64_tr_b16 v[218:219], v192 offset:0x3800
	s_cbranch_vccnz .LBB0_230

; #define SBAR() __builtin_amdgcn_sched_barrier(0)
; #define SLOAD_A(k0) do { vs0a = *reinterpret_cast<const bf16x8*>(&Vh[(long)((k0) + sr) * LDK + sc]); vs1a = *reinterpret_cast<const bf16x8*>(&Vh[(long)((k0) + 32 + sr) * LDK + sc]); KLOAD(ks0a, ks1a, k0); } while (0)
; __device__ __forceinline__ void finishSM(f32x16& p0, f32x16& p1, float alpha, float& l_reg, bf16x8& pa0, bf16x8& pa1, bf16x8& pa2, bf16x8& pa3) {
; #pragma unroll
;   for (int r = 0; r < 16; ++r) p1[r] = __builtin_amdgcn_exp2f(p1[r]);
;   float ps = 0;
; #pragma unroll
;   for (int r = 0; r < 16; ++r) ps += p0[r];
; #pragma unroll
;   for (int r = 0; r < 16; ++r) ps += p1[r];
;   { auto rr = __builtin_amdgcn_permlane32_swap(__float_as_uint(ps), __float_as_uint(ps), false, false);
;     ps = __uint_as_float(rr[0]) + __uint_as_float(rr[1]); }
;   l_reg = l_reg * alpha + ps;
;     ...
;   PK4(p0, 0, pa0); PK4(p0, 8, pa1); PK4(p1, 0, pa2); PK4(p1, 8, pa3);
;     ...
; }
; template <int ND0>
; __device__ __forceinline__ void qkt(f32x16& p0, f32x16& p1, const char* Ks, const bf16x8* qr, int r32, int hi) {
;   p0 = f32x16{}; p1 = f32x16{};
; #pragma unroll
;   for (int d0 = 0; d0 < ND0; ++d0) { int cb = (d0 * 16 + hi * 8) * 2;
;     bf16x8 b0 = *reinterpret_cast<const bf16x8*>(Ks + KSWZ(r32, cb));
;     bf16x8 b1 = *reinterpret_cast<const bf16x8*>(Ks + KSWZ(32 + r32, cb));
;     p0 = __builtin_amdgcn_mfma_f32_32x32x16_bf16(b0, qr[d0], p0, 0, 0, 0);
;     p1 = __builtin_amdgcn_mfma_f32_32x32x16_bf16(b1, qr[d0], p1, 0, 0, 0); }
; }
; template <int ND0, int LDQ, int LDK, int LDO> ...
;     ...
;     SBAR(); qkt<ND0>(pA0, pA1, Kq0, qr, r32, hi);
;     finishSM(pB0, pB1, alB, l_reg, pa0, pa1, pa2, pa3); SBAR();
;     if (j + 3 < NT) SLOAD_A((j + 3) * KVBLK); SBAR();
.LBB0_220:
	ds_read_b128 v[222:225], v198 offset:32768
	ds_read_b128 v[244:247], v198 offset:40960
	v_exp_f32_e32 v226, v84
	v_exp_f32_e32 v227, v85
	s_waitcnt lgkmcnt(2)
	v_mfma_f32_32x32x16_bf16 v[96:111], v[64:67], v[126:129], 0
	v_exp_f32_e32 v234, v86
	v_exp_f32_e32 v235, v87
	v_exp_f32_e32 v236, v88
	v_exp_f32_e32 v237, v89
	v_exp_f32_e32 v238, v90
	v_exp_f32_e32 v239, v91
	v_exp_f32_e32 v240, v92
	v_mfma_f32_32x32x16_bf16 v[64:79], v[68:71], v[126:129], 0
	v_exp_f32_e32 v241, v93
	v_exp_f32_e32 v95, v95
	s_waitcnt lgkmcnt(0)
	v_mfma_f32_32x32x16_bf16 v[96:111], v[222:225], v[122:125], v[96:111]
	v_mfma_f32_32x32x16_bf16 v[64:79], v[244:247], v[122:125], v[64:79]
	ds_read_b128 v[130:133], v199 offset:32768
	ds_read_b128 v[134:137], v199 offset:40960
	s_waitcnt lgkmcnt(0)
	v_mfma_f32_32x32x16_bf16 v[96:111], v[130:133], v[118:121], v[96:111]
	v_mfma_f32_32x32x16_bf16 v[64:79], v[134:137], v[118:121], v[64:79]
	ds_read_b128 v[138:141], v196 offset:32768
	ds_read_b128 v[244:247], v196 offset:40960
	s_waitcnt lgkmcnt(0)
	v_mfma_f32_32x32x16_bf16 v[96:111], v[138:141], v[114:117], v[96:111]
	v_exp_f32_e32 v222, v80
	v_add_f32_e32 v80, v221, v219
	v_add_f32_e32 v80, v217, v80
	v_add_f32_e32 v80, v220, v80
	v_add_f32_e32 v80, v215, v80
	v_add_f32_e32 v80, v218, v80
	v_add_f32_e32 v80, v214, v80
	v_add_f32_e32 v80, v216, v80
	v_add_f32_e32 v80, v211, v80
	v_add_f32_e32 v80, v213, v80
	v_add_f32_e32 v80, v209, v80
	v_add_f32_e32 v80, v212, v80
	v_add_f32_e32 v80, v207, v80
	v_exp_f32_e32 v223, v81
	v_add_f32_e32 v80, v210, v80
	v_exp_f32_e32 v224, v82
	v_add_f32_e32 v80, v206, v80
	v_exp_f32_e32 v225, v83
	v_add_f32_e32 v80, v208, v80
	v_add_f32_e32 v80, v222, v80
	v_add_f32_e32 v80, v223, v80
	v_add_f32_e32 v80, v224, v80
	v_add_f32_e32 v80, v225, v80
	v_add_f32_e32 v80, v226, v80
	v_add_f32_e32 v80, v227, v80
	v_add_f32_e32 v80, v234, v80
	v_add_f32_e32 v80, v235, v80
	v_add_f32_e32 v80, v236, v80
	v_add_f32_e32 v80, v237, v80
	v_mfma_f32_32x32x16_bf16 v[64:79], v[244:247], v[114:117], v[64:79]
	v_exp_f32_e32 v244, v94
	v_add_f32_e32 v80, v238, v80
	v_add_f32_e32 v80, v239, v80
	v_add_f32_e32 v80, v240, v80
	v_add_f32_e32 v80, v241, v80
	v_add_f32_e32 v80, v244, v80
	v_add_f32_e32 v204, v95, v80
	v_mov_b32_e32 v205, v204
	v_cvt_pk_bf16_f32 v80, v219, v221
	v_cvt_pk_bf16_f32 v81, v217, v220
	v_cvt_pk_bf16_f32 v82, v215, v218
	v_cvt_pk_bf16_f32 v83, v214, v216
	v_cvt_pk_bf16_f32 v84, v211, v213
	v_cvt_pk_bf16_f32 v85, v209, v212
	v_cvt_pk_bf16_f32 v86, v207, v210
	v_cvt_pk_bf16_f32 v87, v206, v208
	v_cvt_pk_bf16_f32 v88, v222, v223
	v_cvt_pk_bf16_f32 v89, v224, v225
	v_cvt_pk_bf16_f32 v90, v226, v227
	v_cvt_pk_bf16_f32 v91, v234, v235
	v_cvt_pk_bf16_f32 v92, v236, v237
	v_cvt_pk_bf16_f32 v93, v238, v239
	v_cvt_pk_bf16_f32 v94, v240, v241
	v_cvt_pk_bf16_f32 v95, v244, v95
	v_permlane32_swap_b32_e32 v204, v205
	v_permlane32_swap_b32_e32 v80, v82
	v_permlane32_swap_b32_e32 v81, v83
	v_permlane32_swap_b32_e32 v84, v86
	v_permlane32_swap_b32_e32 v85, v87
	v_permlane32_swap_b32_e32 v88, v90
	v_permlane32_swap_b32_e32 v89, v91
	v_permlane32_swap_b32_e32 v92, v94
	v_permlane32_swap_b32_e32 v93, v95
	s_cmp_ge_u32 s40, s39
	s_cselect_b64 s[18:19], -1, 0
	s_and_b64 vcc, exec, s[18:19]
	s_cbranch_vccnz .Ldiff_pf_skip
	global_load_dwordx4 v[130:133], v[172:173], off
	v_lshl_add_u64 v[174:175], v[172:173], 0, s[34:35]
	global_load_dwordx4 v[134:137], v[174:175], off
	global_load_dwordx4 v[138:141], v[170:171], off offset:2048
	v_lshl_add_u64 v[172:173], v[172:173], 0, s[46:47]
	v_lshl_add_u64 v[170:171], v[170:171], 0, s[46:47]
